# same-XCD census guard + plain ring stores, SSD2 state loads prefetched one trip ahead, DONE atomic deferred
# baseline (speedup 1.0000x reference)
; #define LAS __attribute__((address_space(3)))
; __device__ __forceinline__ unsigned xb_add(unsigned* p, unsigned v) { return __hip_atomic_fetch_add(p, v, __ATOMIC_RELAXED, __HIP_MEMORY_SCOPE_AGENT); }
; __device__ __forceinline__ unsigned xb_xcc_id() { return (unsigned)__builtin_amdgcn_s_getreg((3 << 11) | 20) & 0xFu; }
; __device__ __forceinline__ XcdBarrier xcd_barrier_post(unsigned* bar, volatile LAS unsigned* st) {
;     XcdBarrier b; b.bar = bar; b.x = xb_xcc_id(); b.st = st;
;     if (threadIdx.x == 0) (void)xb_add(&bar[XB_XCNT(b.x)], 1u);
;     return b;
; }
; __global__ void __launch_bounds__(512, 2) k_mega(Params p) {
;     ...
;     volatile LAS unsigned* xbst = (volatile LAS unsigned*)(lds + LDS_BYTES_C - 64);
;     if (threadIdx.x < 2) xbst[threadIdx.x] = 0u;
;     __syncthreads();
;     const XcdBarrier xbar = xcd_barrier_post((unsigned*)(p.ws + WS_CTL + CTL_XBAR), xbst);
_Z6k_mega6Params:
	s_mov_b32 s89, s2
	s_load_dwordx8 s[8:15], s[0:1], 0xc0
	s_load_dword s2, s[0:1], 0xe8
	s_load_dwordx2 s[60:61], s[0:1], 0xe0
	s_add_u32 s4, s0, 0xe0
	v_and_b32_e32 v194, 0x3ff, v0
	s_addc_u32 s5, s1, 0
	s_waitcnt lgkmcnt(0)
	v_writelane_b32 v253, s2, 0
	v_cmp_gt_u32_e32 vcc, 2, v194
	s_and_saveexec_b64 s[2:3], vcc
	v_lshl_add_u32 v1, v194, 2, 0
	v_add_u32_e32 v1, 0x27fc0, v1
	v_mov_b32_e32 v2, 0
	ds_write_b32 v1, v2
	s_or_b64 exec, exec, s[2:3]
	s_waitcnt lgkmcnt(0)
	s_barrier
	s_add_u32 s96, s14, 0xb0000
	s_getreg_b32 s2, hwreg(HW_REG_XCC_ID, 0, 4)
	s_addc_u32 s97, s15, 0
	s_and_b32 s2, s2, 15
	v_writelane_b32 v253, s2, 1
	v_cmp_eq_u32_e64 s[6:7], 0, v194
	s_mov_b64 s[2:3], exec
	s_nop 0
	v_writelane_b32 v253, s6, 2
	s_nop 1
	v_writelane_b32 v253, s7, 3
	s_and_b64 s[6:7], s[2:3], s[6:7]
	s_mov_b64 exec, s[6:7]
	s_cbranch_execz .LBB0_5
	s_mov_b64 s[6:7], exec
	v_mbcnt_lo_u32_b32 v1, s6, 0
	v_mbcnt_hi_u32_b32 v1, s7, v1
	v_cmp_eq_u32_e32 vcc, 0, v1
	s_and_b64 s[16:17], exec, vcc
	s_mov_b64 exec, s[16:17]
	s_cbranch_execz .LBB0_5
	v_readlane_b32 s16, v253, 1
	s_lshl_b32 s16, s16, 8
	s_bcnt1_i32_b64 s6, s[6:7]
	v_mov_b32_e32 v1, s16
	v_mov_b32_e32 v2, s6
	global_atomic_add v1, v2, s[96:97] offset:1024
	v_readlane_b32 s98, v253, 1
	s_and_b32 s99, s89, 7
	s_lshl_b32 s99, s99, 2
	s_lshl_b32 s98, 1, s98
	s_add_i32 s99, s99, 0x10000
	v_mov_b32_e32 v1, s99
	v_mov_b32_e32 v2, s98
	global_atomic_or v1, v2, s[96:97]

; #define LAS __attribute__((address_space(3)))
; #define RD_PREFETCH_A(cc) do { const int soA_ = (b * SEQ + 16 * (cc)) * 256; \
;                 _Pragma("unroll") for (int ks = 0; ks < 3; ++ks) { nAW[ks] = __builtin_bit_cast(bf16x8, __builtin_amdgcn_raw_buffer_load_b128(rsWS, voA + 64 * ks, (int)WS_AW + soA_, 0)); nAA[ks] = __builtin_bit_cast(bf16x8, __builtin_amdgcn_raw_buffer_load_b128(rsWS, voA + 64 * ks, (int)WS_AA + soA_, 0)); } } while (0)
; __device__ void phase_rwkv_dist(const Params& p, LAS unsigned char* lds, int wg, int nwg) {
;     ...
;             LAS const unsigned char* wb = lds + RC_W2H + (r * 104 + 8 * q) * 2;
;             LAS const float* cq = cst + 4 * q;
;             asm volatile("" : "+v"(wb), "+v"(cq));
;             { const int c0 = 6 * qw + pw; if (c0 < RC_NCHK) { RD_PREFETCH_A(c0); } }
;             for (int cj = 0; cj < 2 * ((RC_NCHK + 23) / 24); ++cj) {
;                 const int ci = 24 * (cj >> 1) + 6 * qw + pw + 3 * (cj & 1); if (ci >= RC_NCHK) continue;
;                 const int cn = 24 * ((cj + 1) >> 1) + 6 * qw + pw + 3 * ((cj + 1) & 1);
;                 RD_PREFETCH_R(ci);
.LBB0_648:
	s_and_b32 s91, s51, 7
	s_lshl_b32 s91, s91, 2
	s_add_i32 s91, s91, 0x90000
	v_mov_b32_e32 v182, s91
	global_load_dword v182, v182, s[96:97] sc1
	s_waitcnt vmcnt(0)
	v_readfirstlane_b32 s91, v182
	s_add_i32 s84, s91, -1
	s_and_b32 s84, s84, s91
	s_cmp_eq_u32 s84, 0
	s_cselect_b32 s91, 1, 0
	v_mov_b32_e32 v252, 0
	s_mov_b32 s90, -1
	v_mov_b64_e32 v[42:43], v[6:7]
	v_mov_b64_e32 v[46:47], v[10:11]
	v_mov_b64_e32 v[50:51], v[14:15]
	v_mov_b64_e32 v[30:31], v[18:19]
	v_mov_b64_e32 v[34:35], v[22:23]
	v_mov_b64_e32 v[38:39], v[26:27]
	s_andn2_b64 vcc, exec, s[2:3]
	v_mov_b64_e32 v[40:41], v[4:5]
	v_mov_b64_e32 v[44:45], v[8:9]
	v_mov_b64_e32 v[48:49], v[12:13]
	v_mov_b64_e32 v[28:29], v[16:17]
	v_mov_b64_e32 v[32:33], v[20:21]
	v_mov_b64_e32 v[36:37], v[24:25]
	s_cbranch_vccnz .LBB0_650
	s_lshl_b32 s1, s16, 12
	s_lshl_b32 s17, s0, 21
	s_add_i32 s1, s17, s1
	s_add_i32 s2, s1, 0x100000
	s_add_i32 s1, s1, 0x500000
	buffer_load_dwordx4 v[28:31], v190, s[52:55], s2 offen
	buffer_load_dwordx4 v[40:43], v190, s[52:55], s1 offen
	buffer_load_dwordx4 v[32:35], v205, s[52:55], s2 offen
	buffer_load_dwordx4 v[44:47], v205, s[52:55], s1 offen
	buffer_load_dwordx4 v[36:39], v206, s[52:55], s2 offen
	buffer_load_dwordx4 v[48:51], v206, s[52:55], s1 offen
	s_lshl_b32 s85, s94, 20
	s_lshl_b32 s84, s16, 11
	s_add_i32 s85, s85, s84
	s_add_i32 s88, s85, 0xffffff80
	s_cmp_gt_i32 s85, 0
	s_cselect_b32 s88, s88, 0
	s_cselect_b32 s89, 0, 0xffffff80
	v_add_u32_e32 v178, s89, v191
	v_add_u32_e32 v179, s89, v207
	v_add_u32_e32 v180, s89, v208
	v_add_u32_e32 v181, s89, v209
	s_add_i32 s86, s85, 0x13800000
	s_add_i32 s87, s85, 0x17800000
	s_add_i32 s89, s88, 0x17800000
	s_add_i32 s88, s88, 0x13800000
	buffer_load_dwordx2 v[220:221], v191, s[52:55], s86 offen
	buffer_load_dwordx2 v[222:223], v207, s[52:55], s86 offen
	buffer_load_dwordx2 v[224:225], v207, s[52:55], s87 offen
	buffer_load_dwordx2 v[226:227], v191, s[52:55], s87 offen
	buffer_load_dwordx2 v[228:229], v178, s[52:55], s88 offen
	buffer_load_dwordx2 v[230:231], v179, s[52:55], s88 offen
	buffer_load_dwordx2 v[232:233], v179, s[52:55], s89 offen
	buffer_load_dwordx2 v[234:235], v178, s[52:55], s89 offen
	buffer_load_dwordx2 v[236:237], v208, s[52:55], s86 offen
	buffer_load_dwordx2 v[238:239], v209, s[52:55], s86 offen
	buffer_load_dwordx2 v[240:241], v209, s[52:55], s87 offen
	buffer_load_dwordx2 v[242:243], v208, s[52:55], s87 offen
	buffer_load_dwordx2 v[244:245], v180, s[52:55], s88 offen
	buffer_load_dwordx2 v[246:247], v181, s[52:55], s88 offen
	buffer_load_dwordx2 v[248:249], v181, s[52:55], s89 offen
	buffer_load_dwordx2 v[250:251], v180, s[52:55], s89 offen

; #define LAS __attribute__((address_space(3)))
; __device__ void phase_rwkv_dist(const Params& p, LAS unsigned char* lds, int wg, int nwg) {
;     ...
;                 const float rn = __builtin_amdgcn_rsqf(fmaxf(ss, 1e-24f));
;                 if (ci >= RD_NG) { unsigned sp = 0; while (!dead && __hip_atomic_load(DONE + bh * 512 + (ci - RD_NG), __ATOMIC_RELAXED, __HIP_MEMORY_SCOPE_AGENT) < 256u) { __builtin_amdgcn_s_sleep(2); if (++sp > RD_SPIN_MAX) { if (lane == 0) atomicAdd(ERR, 1u); dead = true; } } }
;                 const int so = ringbase + (ci % RD_NG) * RD_SLOTG;
;                 bf16x4 qa[4], qb[4], qk[4], qr[4];
; #pragma unroll
;                 for (int nt = 0; nt < 4; ++nt) {
;                     const f32x4 w0 = *(LAS const f32x4*)(cq + 0 * 64 + 16 * nt), a0 = *(LAS const f32x4*)(cq + 1 * 64 + 16 * nt);
;                     f32x4 lw, ag;
; #pragma unroll
;                     for (int i = 0; i < 4; ++i) { lw[i] = -0.60653066f * __builtin_amdgcn_rcpf(1.f + __expf(-(w0[i] + accw[nt][i]))); ag[i] = __builtin_amdgcn_rcpf(1.f + __expf(-(a0[i] + acca[nt][i]))); }
;                     const f32x4 mur = *(LAS const f32x4*)(cq + 5 * 64 + 16 * nt), muk = *(LAS const f32x4*)(cq + 6 * 64 + 16 * nt), kkc = *(LAS const f32x4*)(cq + 2 * 64 + 16 * nt), kac = *(LAS const f32x4*)(cq + 3 * 64 + 16 * nt), rkc = *(LAS const f32x4*)(cq + 4 * 64 + 16 * nt);
;                     const f32x4 rc = up4(nX[nt][0]), kc = up4(nX[4 + nt][0]); f32x4 rp = up4(nX[nt][1]), kq = up4(nX[4 + nt][1]); if (first) { rp = zero4; kq = zero4; }
;                     const f32x4 r4 = rc + (rp - rc) * mur, k4 = kc + (kq - kc) * muk;
;                     const f32x4 kn = k4 * kkc * rn, kp = k4 * (1.f + (ag - 1.f) * kac);
;                     const f32x4 b4_ = r4 * kp * rkc; bo += (b4_.x + b4_.y) + (b4_.z + b4_.w);
;                     f32x4 G = lw;
; #pragma unroll
;                     for (int i = 0; i < 4; ++i) { float g = G[i]; g += dpp_f<0x111>(g); g += dpp_f<0x112>(g); g += dpp_f<0x114>(g); g += dpp_f<0x118>(g); G[i] = g; }
;                     f32x4 eG, eGx, eI;
; #pragma unroll
;                     for (int i = 0; i < 4; ++i) { eG[i] = __expf(G[i]); eGx[i] = __builtin_bit_cast(float, __builtin_amdgcn_update_dpp(0x3F800000, __builtin_bit_cast(int, eG[i]), 0x111, 0xf, 0xf, false)); eI[i] = __builtin_amdgcn_rcpf(eG[i]); }
.LBB0_651:
	s_waitcnt lgkmcnt(0)
	v_add_f32_e32 v0, v0, v100
	ds_read_b128 v[100:103], v139
	ds_read_b128 v[142:145], v139 offset:256
	v_lshlrev_b32_e32 v168, 16, v64
	v_and_b32_e32 v64, 0xffff0000, v64
	v_lshlrev_b32_e32 v169, 16, v65
	s_waitcnt lgkmcnt(1)
	v_add_f32_e32 v52, v52, v100
	v_mul_f32_e32 v52, 0xbfb8aa3b, v52
	v_exp_f32_e32 v52, v52
	v_and_b32_e32 v65, 0xffff0000, v65
	v_lshlrev_b32_e32 v166, 16, v60
	v_and_b32_e32 v167, 0xffff0000, v60
	v_add_f32_e32 v52, 1.0, v52
	v_rcp_f32_e32 v157, v52
	s_waitcnt lgkmcnt(0)
	v_add_f32_e32 v52, v56, v142
	v_mul_f32_e32 v52, 0xbfb8aa3b, v52
	v_exp_f32_e32 v52, v52
	v_lshlrev_b32_e32 v60, 16, v61
	v_and_b32_e32 v61, 0xffff0000, v61
	v_cndmask_b32_e64 v177, v169, 0, s[38:39]
	v_add_f32_e32 v52, 1.0, v52
	v_rcp_f32_e32 v146, v52
	v_add_f32_e32 v52, v53, v101
	v_mul_f32_e32 v52, 0xbfb8aa3b, v52
	v_exp_f32_e32 v52, v52
	v_cndmask_b32_e64 v169, v65, 0, s[38:39]
	v_cndmask_b32_e64 v168, v168, 0, s[38:39]
	v_cndmask_b32_e64 v64, v64, 0, s[38:39]
	v_add_f32_e32 v52, 1.0, v52
	v_rcp_f32_e32 v170, v52
	v_add_f32_e32 v52, v57, v143
	v_mul_f32_e32 v52, 0xbfb8aa3b, v52
	v_exp_f32_e32 v52, v52
	v_sub_f32_e32 v65, v64, v167
	v_sub_f32_e32 v64, v168, v166
	v_sub_f32_e32 v169, v169, v61
	v_add_f32_e32 v52, 1.0, v52
	v_rcp_f32_e32 v147, v52
	v_add_f32_e32 v52, v54, v102
	v_mul_f32_e32 v52, 0xbfb8aa3b, v52
	v_exp_f32_e32 v52, v52
	v_sub_f32_e32 v168, v177, v60
	v_mul_f32_e32 v164, 0xbf1b4598, v157
	v_mul_f32_e32 v171, 0xbf1b4598, v170
	v_add_f32_e32 v52, 1.0, v52
	v_rcp_f32_e32 v172, v52
	v_add_f32_e32 v52, v58, v144
	v_mul_f32_e32 v52, 0xbfb8aa3b, v52
	v_exp_f32_e32 v52, v52
	v_mul_f32_e32 v173, 0xbf1b4598, v172
	v_max_f32_e32 v0, 0x179abe15, v0
	v_rsq_f32_e32 v0, v0
	v_add_f32_e32 v52, 1.0, v52
	v_rcp_f32_e32 v162, v52
	v_add_f32_e32 v52, v55, v103
	v_mul_f32_e32 v52, 0xbfb8aa3b, v52
	v_exp_f32_e32 v52, v52
	s_lshl_b32 s2, s62, 4
	s_ashr_i32 s3, s2, 31
	v_lshl_add_u64 v[108:109], v[2:3], 0, s[2:3]
	v_add_f32_e32 v52, 1.0, v52
	v_rcp_f32_e32 v174, v52
	v_add_f32_e32 v52, v59, v145
	v_mul_f32_e32 v52, 0xbfb8aa3b, v52
	v_exp_f32_e32 v52, v52
	v_mul_f32_e32 v176, 0xbf1b4598, v174
	s_mul_hi_i32 s2, s62, 0x92492493
	s_add_i32 s2, s2, s62
	v_add_f32_e32 v52, 1.0, v52
	v_rcp_f32_e32 v163, v52
	ds_read_b128 v[52:55], v139 offset:1280
	ds_read_b128 v[56:59], v139 offset:1536
	ds_read_b128 v[100:103], v139 offset:512
	ds_read_b128 v[142:145], v139 offset:768
	ds_read_b128 v[158:161], v139 offset:1024
	s_waitcnt lgkmcnt(4)
	v_pk_fma_f32 v[54:55], v[168:169], v[54:55], v[60:61]
	v_pk_fma_f32 v[60:61], v[64:65], v[52:53], v[166:167]
	s_waitcnt lgkmcnt(3)
	v_pk_fma_f32 v[52:53], v[96:97], v[58:59], v[94:95]
	v_pk_fma_f32 v[56:57], v[98:99], v[56:57], v[92:93]
	v_pk_add_f32 v[92:93], v[162:163], -1.0 op_sel_hi:[1,0]
	v_pk_add_f32 v[94:95], v[146:147], -1.0 op_sel_hi:[1,0]
	s_waitcnt lgkmcnt(1)
	v_pk_fma_f32 v[92:93], v[144:145], v[92:93], 1.0 op_sel_hi:[1,1,0]
	v_pk_fma_f32 v[94:95], v[142:143], v[94:95], 1.0 op_sel_hi:[1,1,0]
	v_pk_mul_f32 v[64:65], v[100:101], v[56:57]
	v_pk_mul_f32 v[96:97], v[52:53], v[92:93]
	v_pk_mul_f32 v[56:57], v[56:57], v[94:95]
	v_pk_mul_f32 v[58:59], v[102:103], v[52:53]
	v_pk_mul_f32 v[52:53], v[60:61], v[56:57]
	v_pk_mul_f32 v[92:93], v[54:55], v[96:97]
	s_waitcnt lgkmcnt(0)
	v_pk_mul_f32 v[52:53], v[158:159], v[52:53]
	v_pk_mul_f32 v[92:93], v[160:161], v[92:93]
	v_add_f32_e32 v52, v52, v53
	v_add_f32_e32 v53, v92, v93
	v_add_f32_e32 v101, v52, v53
	v_mov_b32_dpp v52, v164 row_shr:1 row_mask:0xf bank_mask:0xf bound_ctrl:1
	v_fmac_f32_e32 v52, 0xbf1b4598, v157
	v_mov_b32_e32 v100, 1.0
	v_pk_mul_f32 v[98:99], v[0:1], v[64:65] op_sel_hi:[0,1]
	v_add_f32_dpp v52, v52, v52 row_shr:2 row_mask:0xf bank_mask:0xf bound_ctrl:1
	v_pk_fma_f32 v[64:65], v[0:1], v[64:65], 0 op_sel_hi:[0,1,0] neg_lo:[1,0,0] neg_hi:[1,0,0]
	s_lshr_b32 s3, s2, 31
	v_add_f32_dpp v52, v52, v52 row_shr:4 row_mask:0xf bank_mask:0xf bound_ctrl:1
	s_lshr_b32 s2, s2, 5
	s_add_i32 s2, s2, s3
	v_add_f32_dpp v92, v52, v52 row_shr:8 row_mask:0xf bank_mask:0xf bound_ctrl:1
	v_mov_b32_dpp v52, v171 row_shr:1 row_mask:0xf bank_mask:0xf bound_ctrl:1
	v_fmac_f32_e32 v52, 0xbf1b4598, v170
	v_mul_f32_e32 v92, 0x3fb8aa3b, v92
	v_exp_f32_e32 v92, v92
	v_add_f32_dpp v52, v52, v52 row_shr:2 row_mask:0xf bank_mask:0xf bound_ctrl:1
	s_mul_i32 s2, s2, 56
	s_sub_i32 s2, s62, s2
	v_add_f32_dpp v52, v52, v52 row_shr:4 row_mask:0xf bank_mask:0xf bound_ctrl:1
	v_rcp_f32_e32 v102, v92
	v_mov_b32_dpp v100, v92 row_shr:1 row_mask:0xf bank_mask:0xf
	v_add_f32_dpp v93, v52, v52 row_shr:8 row_mask:0xf bank_mask:0xf bound_ctrl:1
	v_mov_b32_dpp v52, v173 row_shr:1 row_mask:0xf bank_mask:0xf bound_ctrl:1
	v_fmac_f32_e32 v52, 0xbf1b4598, v172
	v_mul_f32_e32 v93, 0x3fb8aa3b, v93
	v_exp_f32_e32 v93, v93
	v_add_f32_dpp v52, v52, v52 row_shr:2 row_mask:0xf bank_mask:0xf bound_ctrl:1
	v_pk_mul_f32 v[64:65], v[64:65], v[100:101] op_sel_hi:[1,0]
	s_mulk_i32 s2, 0x2900
	v_add_f32_dpp v52, v52, v52 row_shr:4 row_mask:0xf bank_mask:0xf bound_ctrl:1
	v_rcp_f32_e32 v103, v93
	v_cvt_pk_bf16_f32 v64, v64, v65
	v_add_f32_dpp v94, v52, v52 row_shr:8 row_mask:0xf bank_mask:0xf bound_ctrl:1
	v_mov_b32_dpp v52, v176 row_shr:1 row_mask:0xf bank_mask:0xf bound_ctrl:1
	v_fmac_f32_e32 v52, 0xbf1b4598, v174
	v_mul_f32_e32 v94, 0x3fb8aa3b, v94
	v_exp_f32_e32 v94, v94
	v_add_f32_dpp v52, v52, v52 row_shr:2 row_mask:0xf bank_mask:0xf bound_ctrl:1
	v_pk_mul_f32 v[56:57], v[56:57], v[102:103]
	s_add_i32 s2, s2, s80
	v_add_f32_dpp v52, v52, v52 row_shr:4 row_mask:0xf bank_mask:0xf bound_ctrl:1
	v_rcp_f32_e32 v144, v94
	v_cvt_pk_bf16_f32 v56, v56, v57
	v_add_f32_dpp v95, v52, v52 row_shr:8 row_mask:0xf bank_mask:0xf bound_ctrl:1
	v_mul_f32_e32 v95, 0x3fb8aa3b, v95
	v_exp_f32_e32 v95, v95
	v_pk_mul_f32 v[52:53], v[0:1], v[58:59] op_sel_hi:[0,1]
	v_pk_fma_f32 v[58:59], v[0:1], v[58:59], 0 op_sel_hi:[0,1,0] neg_lo:[1,0,0] neg_hi:[1,0,0]
	v_pk_mul_f32 v[58:59], v[58:59], v[100:101] op_sel_hi:[1,0]
	v_rcp_f32_e32 v145, v95
	v_cvt_pk_bf16_f32 v65, v58, v59
	v_pk_mul_f32 v[58:59], v[98:99], v[146:147]
	v_pk_mul_f32 v[52:53], v[52:53], v[162:163]
	s_add_i32 s6, s2, 0x2800
	v_pk_mul_f32 v[98:99], v[52:53], v[144:145]
	v_pk_mul_f32 v[52:53], v[58:59], v[102:103]
	v_pk_mul_f32 v[58:59], v[96:97], v[144:145]
	v_cvt_pk_bf16_f32 v52, v52, v53
	v_cvt_pk_bf16_f32 v53, v98, v99
	v_cvt_pk_bf16_f32 v57, v58, v59
	v_pk_mul_f32 v[54:55], v[54:55], v[94:95]
	v_pk_mul_f32 v[58:59], v[60:61], v[92:93]
	s_cmp_eq_u32 s91, 0
	s_cbranch_scc1 .Lrst0s
	buffer_store_dwordx4 v[92:95], v210, s[52:55], s6 offen
	s_branch .Lrst0d
; #define LAS __attribute__((address_space(3)))
; #define MFMA16(a, b, c) __builtin_amdgcn_mfma_f32_16x16x16bf16_1k(a, b, c, 0, 0, 0)
; __device__ void phase_rwkv_dist(const Params& p, LAS unsigned char* lds, int wg, int nwg) {
;     ...
;                 for (int nt = 0; nt < 4; ++nt) {
;                     const f32x4 w0 = *(LAS const f32x4*)(cq + 0 * 64 + 16 * nt), a0 = *(LAS const f32x4*)(cq + 1 * 64 + 16 * nt);
;                     f32x4 lw, ag;
; #pragma unroll
;                     for (int i = 0; i < 4; ++i) { lw[i] = -0.60653066f * __builtin_amdgcn_rcpf(1.f + __expf(-(w0[i] + accw[nt][i]))); ag[i] = __builtin_amdgcn_rcpf(1.f + __expf(-(a0[i] + acca[nt][i]))); }
;                     const f32x4 mur = *(LAS const f32x4*)(cq + 5 * 64 + 16 * nt), muk = *(LAS const f32x4*)(cq + 6 * 64 + 16 * nt), kkc = *(LAS const f32x4*)(cq + 2 * 64 + 16 * nt), kac = *(LAS const f32x4*)(cq + 3 * 64 + 16 * nt), rkc = *(LAS const f32x4*)(cq + 4 * 64 + 16 * nt);
;                     const f32x4 rc = up4(nX[nt][0]), kc = up4(nX[4 + nt][0]); f32x4 rp = up4(nX[nt][1]), kq = up4(nX[4 + nt][1]); if (first) { rp = zero4; kq = zero4; }
;                     const f32x4 r4 = rc + (rp - rc) * mur, k4 = kc + (kq - kc) * muk;
;                     const f32x4 kn = k4 * kkc * rn, kp = k4 * (1.f + (ag - 1.f) * kac);
;                     const f32x4 b4_ = r4 * kp * rkc; bo += (b4_.x + b4_.y) + (b4_.z + b4_.w);
;                     f32x4 G = lw;
; #pragma unroll
;                     for (int i = 0; i < 4; ++i) { float g = G[i]; g += dpp_f<0x111>(g); g += dpp_f<0x112>(g); g += dpp_f<0x114>(g); g += dpp_f<0x118>(g); G[i] = g; }
;                     f32x4 eG, eGx, eI;
; #pragma unroll
;                     for (int i = 0; i < 4; ++i) { eG[i] = __expf(G[i]); eGx[i] = __builtin_bit_cast(float, __builtin_amdgcn_update_dpp(0x3F800000, __builtin_bit_cast(int, eG[i]), 0x111, 0xf, 0xf, false)); eI[i] = __builtin_amdgcn_rcpf(eG[i]); }
;                     qa[nt] = pk4((zero4 - kn) * eGx); qb[nt] = pk4(kn * ag * eI); qk[nt] = pk4(kp * eI); qr[nt] = pk4(r4 * eG);
;                     __builtin_amdgcn_raw_buffer_store_b128(__builtin_bit_cast(u32x4, eG), rsWS, (r == 15) ? (16 * nt + 4 * q) * 4 : 0x7ffffff0, so + 10240, 16);
;                     const f32x4 d1 = MFMA16(qb[nt], ident, zero4), d2 = MFMA16(qk[nt], ident, zero4);
.Lrst0s:
	buffer_store_dwordx4 v[92:95], v210, s[52:55], s6 offen sc1
.Lrst0d:
	v_mfma_f32_16x16x16_bf16 v[92:95], v[52:53], v[150:151], 0
	s_add_i32 s3, s2, 0x1000
	v_cvt_pk_bf16_f32 v60, v58, v59
	v_cvt_pk_bf16_f32 v61, v54, v55
	v_mfma_f32_16x16x16_bf16 v[96:99], v[56:57], v[150:151], 0
	v_lshlrev_b32_e32 v162, 16, v66
	s_nop 2
	v_cvt_pk_bf16_f32 v92, v92, v93
	v_cvt_pk_bf16_f32 v93, v94, v95
	v_and_b32_e32 v66, 0xffff0000, v66
	v_add_f32_e32 v142, 0, v101
	v_cvt_pk_bf16_f32 v94, v96, v97
	v_cvt_pk_bf16_f32 v95, v98, v99
	s_cmp_eq_u32 s91, 0
	s_cbranch_scc1 .Lrst1s
	buffer_store_dwordx4 v[92:95], v196, s[52:55], s3 offen
	s_branch .Lrst1d
.Lrst1s:
	buffer_store_dwordx4 v[92:95], v196, s[52:55], s3 offen sc1
.Lrst1d:
	ds_read_b128 v[92:95], v139 offset:64
	ds_read_b128 v[96:99], v139 offset:320
	v_lshlrev_b32_e32 v160, 16, v62
	v_and_b32_e32 v161, 0xffff0000, v62
	v_lshlrev_b32_e32 v163, 16, v67
	s_waitcnt lgkmcnt(1)
	v_add_f32_e32 v54, v84, v92
	v_add_f32_e32 v55, v85, v93
	v_add_f32_e32 v58, v86, v94
	v_add_f32_e32 v59, v87, v95
	v_mul_f32_e32 v54, 0xbfb8aa3b, v54
	v_mul_f32_e32 v55, 0xbfb8aa3b, v55
	v_mul_f32_e32 v58, 0xbfb8aa3b, v58
	v_mul_f32_e32 v59, 0xbfb8aa3b, v59
	v_exp_f32_e32 v54, v54
	v_exp_f32_e32 v55, v55
	v_exp_f32_e32 v58, v58
	v_exp_f32_e32 v59, v59
	v_add_f32_e32 v54, 1.0, v54
	v_add_f32_e32 v55, 1.0, v55
	v_add_f32_e32 v58, 1.0, v58
	v_add_f32_e32 v59, 1.0, v59
	v_rcp_f32_e32 v143, v54
	s_waitcnt lgkmcnt(0)
	v_add_f32_e32 v54, v88, v96
	v_rcp_f32_e32 v145, v55
	v_add_f32_e32 v55, v89, v97
	v_rcp_f32_e32 v147, v58
	v_add_f32_e32 v58, v90, v98
	v_rcp_f32_e32 v158, v59
	v_add_f32_e32 v59, v91, v99
	v_mul_f32_e32 v54, 0xbfb8aa3b, v54
	v_mul_f32_e32 v55, 0xbfb8aa3b, v55
	v_mul_f32_e32 v58, 0xbfb8aa3b, v58
	v_mul_f32_e32 v59, 0xbfb8aa3b, v59
	v_exp_f32_e32 v54, v54
	v_exp_f32_e32 v55, v55
	v_exp_f32_e32 v58, v58
	v_exp_f32_e32 v59, v59
	v_add_f32_e32 v54, 1.0, v54
	v_add_f32_e32 v55, 1.0, v55
	v_add_f32_e32 v58, 1.0, v58
	v_add_f32_e32 v59, 1.0, v59
	v_rcp_f32_e32 v54, v54
	v_rcp_f32_e32 v55, v55
	v_rcp_f32_e32 v58, v58
	v_rcp_f32_e32 v59, v59
	ds_read_b128 v[84:87], v139 offset:1344
	ds_read_b128 v[88:91], v139 offset:1600
	ds_read_b128 v[92:95], v139 offset:576
	ds_read_b128 v[96:99], v139 offset:832
	ds_read_b128 v[100:103], v139 offset:1088
	v_and_b32_e32 v67, 0xffff0000, v67
	v_cndmask_b32_e64 v162, v162, 0, s[38:39]
	v_cndmask_b32_e64 v66, v66, 0, s[38:39]
	v_lshlrev_b32_e32 v62, 16, v63
	v_and_b32_e32 v63, 0xffff0000, v63
	v_cndmask_b32_e64 v164, v163, 0, s[38:39]
	v_cndmask_b32_e64 v163, v67, 0, s[38:39]
	v_sub_f32_e32 v67, v66, v161
	v_sub_f32_e32 v66, v162, v160
	v_sub_f32_e32 v163, v163, v63
	v_sub_f32_e32 v162, v164, v62
	s_waitcnt lgkmcnt(4)
	v_pk_fma_f32 v[160:161], v[66:67], v[84:85], v[160:161]
	s_waitcnt lgkmcnt(3)
	v_pk_fma_f32 v[84:85], v[136:137], v[88:89], v[130:131]
	v_pk_fma_f32 v[62:63], v[162:163], v[86:87], v[62:63]
	v_pk_fma_f32 v[66:67], v[134:135], v[90:91], v[132:133]
	s_waitcnt lgkmcnt(2)
	v_pk_mul_f32 v[90:91], v[92:93], v[84:85]
	v_pk_add_f32 v[86:87], v[58:59], -1.0 op_sel_hi:[1,0]
	v_pk_add_f32 v[92:93], v[54:55], -1.0 op_sel_hi:[1,0]
	s_waitcnt lgkmcnt(1)
	v_pk_fma_f32 v[86:87], v[98:99], v[86:87], 1.0 op_sel_hi:[1,1,0]
	v_pk_fma_f32 v[92:93], v[96:97], v[92:93], 1.0 op_sel_hi:[1,1,0]
	v_pk_mul_f32 v[88:89], v[94:95], v[66:67]
	v_pk_mul_f32 v[94:95], v[66:67], v[86:87]
	v_pk_mul_f32 v[92:93], v[84:85], v[92:93]
	v_pk_mul_f32 v[84:85], v[62:63], v[94:95]
	v_pk_mul_f32 v[66:67], v[160:161], v[92:93]
	v_mul_f32_e32 v146, 0xbf1b4598, v145
	s_waitcnt lgkmcnt(0)
	v_pk_mul_f32 v[84:85], v[102:103], v[84:85]
	v_pk_mul_f32 v[66:67], v[100:101], v[66:67]
	v_mul_f32_e32 v157, 0xbf1b4598, v147
	v_add_f32_e32 v66, v66, v67
	v_add_f32_e32 v67, v84, v85
	v_mov_b32_dpp v84, v146 row_shr:1 row_mask:0xf bank_mask:0xf bound_ctrl:1
	v_fmac_f32_e32 v84, 0xbf1b4598, v145
	v_mul_f32_e32 v144, 0xbf1b4598, v143
	v_mul_f32_e32 v159, 0xbf1b4598, v158
	v_add_f32_dpp v84, v84, v84 row_shr:2 row_mask:0xf bank_mask:0xf bound_ctrl:1
	v_add_f32_e32 v67, v66, v67
	v_mov_b32_dpp v66, v144 row_shr:1 row_mask:0xf bank_mask:0xf bound_ctrl:1
	v_add_f32_dpp v84, v84, v84 row_shr:4 row_mask:0xf bank_mask:0xf bound_ctrl:1
	v_fmac_f32_e32 v66, 0xbf1b4598, v143
	v_pk_mul_f32 v[96:97], v[0:1], v[88:89] op_sel_hi:[0,1]
	v_add_f32_dpp v85, v84, v84 row_shr:8 row_mask:0xf bank_mask:0xf bound_ctrl:1
	v_mov_b32_dpp v84, v157 row_shr:1 row_mask:0xf bank_mask:0xf bound_ctrl:1
	v_fmac_f32_e32 v84, 0xbf1b4598, v147
	v_add_f32_dpp v66, v66, v66 row_shr:2 row_mask:0xf bank_mask:0xf bound_ctrl:1
	v_mul_f32_e32 v85, 0x3fb8aa3b, v85
	v_add_f32_dpp v84, v84, v84 row_shr:2 row_mask:0xf bank_mask:0xf bound_ctrl:1
	v_add_f32_dpp v66, v66, v66 row_shr:4 row_mask:0xf bank_mask:0xf bound_ctrl:1
	v_exp_f32_e32 v85, v85
	v_add_f32_dpp v84, v84, v84 row_shr:4 row_mask:0xf bank_mask:0xf bound_ctrl:1
	v_add_f32_dpp v66, v66, v66 row_shr:8 row_mask:0xf bank_mask:0xf bound_ctrl:1
	v_mul_f32_e32 v66, 0x3fb8aa3b, v66
	v_add_f32_dpp v86, v84, v84 row_shr:8 row_mask:0xf bank_mask:0xf bound_ctrl:1
	v_mov_b32_dpp v84, v159 row_shr:1 row_mask:0xf bank_mask:0xf bound_ctrl:1
	v_fmac_f32_e32 v84, 0xbf1b4598, v158
	v_mul_f32_e32 v86, 0x3fb8aa3b, v86
	v_exp_f32_e32 v86, v86
	v_add_f32_dpp v84, v84, v84 row_shr:2 row_mask:0xf bank_mask:0xf bound_ctrl:1
	v_rcp_f32_e32 v101, v85
	v_pk_mul_f32 v[98:99], v[0:1], v[90:91] op_sel_hi:[0,1]
	v_add_f32_dpp v84, v84, v84 row_shr:4 row_mask:0xf bank_mask:0xf bound_ctrl:1
	v_rcp_f32_e32 v102, v86
	v_pk_fma_f32 v[88:89], v[0:1], v[88:89], 0 op_sel_hi:[0,1,0] neg_lo:[1,0,0] neg_hi:[1,0,0]
	v_add_f32_dpp v87, v84, v84 row_shr:8 row_mask:0xf bank_mask:0xf bound_ctrl:1
	v_mul_f32_e32 v87, 0x3fb8aa3b, v87
	v_exp_f32_e32 v84, v66
	v_exp_f32_e32 v87, v87
	v_mov_b32_e32 v66, 1.0
	v_pk_fma_f32 v[90:91], v[0:1], v[90:91], 0 op_sel_hi:[0,1,0] neg_lo:[1,0,0] neg_hi:[1,0,0]
	v_rcp_f32_e32 v100, v84
	v_rcp_f32_e32 v103, v87
	v_mov_b32_dpp v66, v84 row_shr:1 row_mask:0xf bank_mask:0xf
	v_pk_mul_f32 v[54:55], v[98:99], v[54:55]
	v_pk_mul_f32 v[58:59], v[96:97], v[58:59]
	v_add_f32_e32 v130, v142, v67
	v_pk_mul_f32 v[88:89], v[88:89], v[66:67] op_sel_hi:[1,0]
	v_pk_mul_f32 v[66:67], v[90:91], v[66:67] op_sel_hi:[1,0]
	v_pk_mul_f32 v[58:59], v[58:59], v[102:103]
	v_pk_mul_f32 v[54:55], v[54:55], v[100:101]
	v_cvt_pk_bf16_f32 v66, v66, v67
	v_cvt_pk_bf16_f32 v67, v88, v89
	v_cvt_pk_bf16_f32 v54, v54, v55
	v_cvt_pk_bf16_f32 v55, v58, v59
	v_pk_mul_f32 v[88:89], v[94:95], v[102:103]
	v_pk_mul_f32 v[58:59], v[92:93], v[100:101]
	s_cmp_eq_u32 s91, 0
	s_cbranch_scc1 .Lrst2s
	buffer_store_dwordx4 v[84:87], v211, s[52:55], s6 offen
	s_branch .Lrst2d
; #define LAS __attribute__((address_space(3)))
; #define MFMA16(a, b, c) __builtin_amdgcn_mfma_f32_16x16x16bf16_1k(a, b, c, 0, 0, 0)
; __device__ void phase_rwkv_dist(const Params& p, LAS unsigned char* lds, int wg, int nwg) {
;     ...
;                 for (int nt = 0; nt < 4; ++nt) {
;                     const f32x4 w0 = *(LAS const f32x4*)(cq + 0 * 64 + 16 * nt), a0 = *(LAS const f32x4*)(cq + 1 * 64 + 16 * nt);
;                     f32x4 lw, ag;
; #pragma unroll
;                     for (int i = 0; i < 4; ++i) { lw[i] = -0.60653066f * __builtin_amdgcn_rcpf(1.f + __expf(-(w0[i] + accw[nt][i]))); ag[i] = __builtin_amdgcn_rcpf(1.f + __expf(-(a0[i] + acca[nt][i]))); }
;                     const f32x4 mur = *(LAS const f32x4*)(cq + 5 * 64 + 16 * nt), muk = *(LAS const f32x4*)(cq + 6 * 64 + 16 * nt), kkc = *(LAS const f32x4*)(cq + 2 * 64 + 16 * nt), kac = *(LAS const f32x4*)(cq + 3 * 64 + 16 * nt), rkc = *(LAS const f32x4*)(cq + 4 * 64 + 16 * nt);
;                     const f32x4 rc = up4(nX[nt][0]), kc = up4(nX[4 + nt][0]); f32x4 rp = up4(nX[nt][1]), kq = up4(nX[4 + nt][1]); if (first) { rp = zero4; kq = zero4; }
;                     const f32x4 r4 = rc + (rp - rc) * mur, k4 = kc + (kq - kc) * muk;
;                     const f32x4 kn = k4 * kkc * rn, kp = k4 * (1.f + (ag - 1.f) * kac);
;                     const f32x4 b4_ = r4 * kp * rkc; bo += (b4_.x + b4_.y) + (b4_.z + b4_.w);
;                     f32x4 G = lw;
; #pragma unroll
;                     for (int i = 0; i < 4; ++i) { float g = G[i]; g += dpp_f<0x111>(g); g += dpp_f<0x112>(g); g += dpp_f<0x114>(g); g += dpp_f<0x118>(g); G[i] = g; }
;                     f32x4 eG, eGx, eI;
; #pragma unroll
;                     for (int i = 0; i < 4; ++i) { eG[i] = __expf(G[i]); eGx[i] = __builtin_bit_cast(float, __builtin_amdgcn_update_dpp(0x3F800000, __builtin_bit_cast(int, eG[i]), 0x111, 0xf, 0xf, false)); eI[i] = __builtin_amdgcn_rcpf(eG[i]); }
;                     qa[nt] = pk4((zero4 - kn) * eGx); qb[nt] = pk4(kn * ag * eI); qk[nt] = pk4(kp * eI); qr[nt] = pk4(r4 * eG);
;                     __builtin_amdgcn_raw_buffer_store_b128(__builtin_bit_cast(u32x4, eG), rsWS, (r == 15) ? (16 * nt + 4 * q) * 4 : 0x7ffffff0, so + 10240, 16);
;                     const f32x4 d1 = MFMA16(qb[nt], ident, zero4), d2 = MFMA16(qk[nt], ident, zero4);
.Lrst2s:
	buffer_store_dwordx4 v[84:87], v211, s[52:55], s6 offen sc1
.Lrst2d:
	v_cvt_pk_bf16_f32 v58, v58, v59
	v_cvt_pk_bf16_f32 v59, v88, v89
	v_pk_mul_f32 v[88:89], v[62:63], v[86:87]
	v_pk_mul_f32 v[62:63], v[160:161], v[84:85]
	v_mfma_f32_16x16x16_bf16 v[84:87], v[54:55], v[150:151], 0
	v_cvt_pk_bf16_f32 v62, v62, v63
	v_cvt_pk_bf16_f32 v63, v88, v89
	v_lshlrev_b32_e32 v100, 16, v118
	v_mfma_f32_16x16x16_bf16 v[88:91], v[58:59], v[150:151], 0
	v_and_b32_e32 v101, 0xffff0000, v118
	s_nop 2
	v_cvt_pk_bf16_f32 v84, v84, v85
	v_cvt_pk_bf16_f32 v85, v86, v87
	v_lshlrev_b32_e32 v102, 16, v119
	v_and_b32_e32 v103, 0xffff0000, v119
	v_cvt_pk_bf16_f32 v86, v88, v89
	v_cvt_pk_bf16_f32 v87, v90, v91
	s_cmp_eq_u32 s91, 0
	s_cbranch_scc1 .Lrst3s
	buffer_store_dwordx4 v[84:87], v197, s[52:55], s3 offen
	s_branch .Lrst3d
.Lrst3s:
	buffer_store_dwordx4 v[84:87], v197, s[52:55], s3 offen sc1
.Lrst3d:
	ds_read_b128 v[84:87], v139 offset:128
	ds_read_b128 v[88:91], v139 offset:384
	v_lshlrev_b32_e32 v118, 16, v120
	v_and_b32_e32 v119, 0xffff0000, v120
	v_lshlrev_b32_e32 v120, 16, v121
	s_waitcnt lgkmcnt(1)
	v_add_f32_e32 v76, v76, v84
	v_mul_f32_e32 v76, 0xbfb8aa3b, v76
	v_exp_f32_e32 v76, v76
	v_and_b32_e32 v121, 0xffff0000, v121
	v_cndmask_b32_e64 v118, v118, 0, s[38:39]
	v_cndmask_b32_e64 v119, v119, 0, s[38:39]
	v_add_f32_e32 v76, 1.0, v76
	v_rcp_f32_e32 v131, v76
	s_waitcnt lgkmcnt(0)
	v_add_f32_e32 v76, v80, v88
	v_mul_f32_e32 v76, 0xbfb8aa3b, v76
	v_exp_f32_e32 v76, v76
	v_cndmask_b32_e64 v120, v120, 0, s[38:39]
	v_cndmask_b32_e64 v121, v121, 0, s[38:39]
	v_sub_f32_e32 v119, v119, v101
	v_add_f32_e32 v76, 1.0, v76
	v_rcp_f32_e32 v96, v76
	v_add_f32_e32 v76, v77, v85
	v_mul_f32_e32 v76, 0xbfb8aa3b, v76
	v_exp_f32_e32 v76, v76
	v_sub_f32_e32 v118, v118, v100
	v_sub_f32_e32 v121, v121, v103
	v_sub_f32_e32 v120, v120, v102
	v_add_f32_e32 v76, 1.0, v76
	v_rcp_f32_e32 v133, v76
	v_add_f32_e32 v76, v81, v89
	v_mul_f32_e32 v76, 0xbfb8aa3b, v76
	v_exp_f32_e32 v76, v76
	v_mul_f32_e32 v132, 0xbf1b4598, v131
	v_mul_f32_e32 v134, 0xbf1b4598, v133
	v_add_f32_e32 v76, 1.0, v76
	v_rcp_f32_e32 v97, v76
	v_add_f32_e32 v76, v78, v86
	v_mul_f32_e32 v76, 0xbfb8aa3b, v76
	v_exp_f32_e32 v76, v76
	s_nop 0
	v_add_f32_e32 v76, 1.0, v76
	v_rcp_f32_e32 v135, v76
	v_add_f32_e32 v76, v82, v90
	v_mul_f32_e32 v76, 0xbfb8aa3b, v76
	v_exp_f32_e32 v76, v76
	v_mul_f32_e32 v136, 0xbf1b4598, v135
	v_add_f32_e32 v76, 1.0, v76
	v_rcp_f32_e32 v98, v76
	v_add_f32_e32 v76, v79, v87
	v_mul_f32_e32 v76, 0xbfb8aa3b, v76
	v_exp_f32_e32 v76, v76
	s_nop 0
	v_add_f32_e32 v76, 1.0, v76
	v_rcp_f32_e32 v137, v76
	v_add_f32_e32 v76, v83, v91
	v_mul_f32_e32 v76, 0xbfb8aa3b, v76
	v_exp_f32_e32 v76, v76
	v_mul_f32_e32 v142, 0xbf1b4598, v137
	v_add_f32_e32 v76, 1.0, v76
	v_rcp_f32_e32 v99, v76
	ds_read_b128 v[76:79], v139 offset:1408
	ds_read_b128 v[80:83], v139 offset:1664
	ds_read_b128 v[84:87], v139 offset:640
	ds_read_b128 v[88:91], v139 offset:896
	ds_read_b128 v[92:95], v139 offset:1152
	s_waitcnt lgkmcnt(4)
	v_pk_fma_f32 v[100:101], v[118:119], v[76:77], v[100:101]
	s_waitcnt lgkmcnt(3)
	v_pk_fma_f32 v[76:77], v[126:127], v[82:83], v[124:125]
	v_pk_fma_f32 v[78:79], v[120:121], v[78:79], v[102:103]
	s_waitcnt lgkmcnt(2)
	v_pk_mul_f32 v[82:83], v[86:87], v[76:77]
	v_pk_add_f32 v[86:87], v[98:99], -1.0 op_sel_hi:[1,0]
	v_pk_add_f32 v[102:103], v[96:97], -1.0 op_sel_hi:[1,0]
	v_pk_fma_f32 v[80:81], v[128:129], v[80:81], v[122:123]
	s_waitcnt lgkmcnt(1)
	v_pk_fma_f32 v[88:89], v[88:89], v[102:103], 1.0 op_sel_hi:[1,1,0]
	v_pk_fma_f32 v[86:87], v[90:91], v[86:87], 1.0 op_sel_hi:[1,1,0]
	v_pk_mul_f32 v[84:85], v[84:85], v[80:81]
	v_pk_mul_f32 v[102:103], v[76:77], v[86:87]
	v_pk_mul_f32 v[80:81], v[80:81], v[88:89]
	v_pk_mul_f32 v[86:87], v[78:79], v[102:103]
	v_pk_mul_f32 v[76:77], v[100:101], v[80:81]
	s_waitcnt lgkmcnt(0)
	v_pk_mul_f32 v[86:87], v[94:95], v[86:87]
	v_pk_mul_f32 v[76:77], v[92:93], v[76:77]
	v_mov_b32_e32 v88, 1.0
	v_add_f32_e32 v76, v76, v77
	v_add_f32_e32 v77, v86, v87
	v_add_f32_e32 v86, v76, v77
	v_mov_b32_dpp v76, v132 row_shr:1 row_mask:0xf bank_mask:0xf bound_ctrl:1
	v_fmac_f32_e32 v76, 0xbf1b4598, v131
	v_pk_mul_f32 v[94:95], v[0:1], v[84:85] op_sel_hi:[0,1]
	v_pk_fma_f32 v[84:85], v[0:1], v[84:85], 0 op_sel_hi:[0,1,0] neg_lo:[1,0,0] neg_hi:[1,0,0]
	v_add_f32_dpp v76, v76, v76 row_shr:2 row_mask:0xf bank_mask:0xf bound_ctrl:1
	v_lshlrev_b32_e32 v123, 16, v106
	v_and_b32_e32 v106, 0xffff0000, v106
	v_add_f32_dpp v76, v76, v76 row_shr:4 row_mask:0xf bank_mask:0xf bound_ctrl:1
	v_lshlrev_b32_e32 v126, 16, v107
	v_and_b32_e32 v107, 0xffff0000, v107
	v_add_f32_dpp v87, v76, v76 row_shr:8 row_mask:0xf bank_mask:0xf bound_ctrl:1
	v_mov_b32_dpp v76, v134 row_shr:1 row_mask:0xf bank_mask:0xf bound_ctrl:1
	v_fmac_f32_e32 v76, 0xbf1b4598, v133
	v_mul_f32_e32 v87, 0x3fb8aa3b, v87
	v_exp_f32_e32 v90, v87
	v_add_f32_dpp v76, v76, v76 row_shr:2 row_mask:0xf bank_mask:0xf bound_ctrl:1
	v_lshlrev_b32_e32 v124, 16, v104
	v_and_b32_e32 v125, 0xffff0000, v104
	v_add_f32_dpp v76, v76, v76 row_shr:4 row_mask:0xf bank_mask:0xf bound_ctrl:1
	v_rcp_f32_e32 v118, v90
	v_mov_b32_dpp v88, v90 row_shr:1 row_mask:0xf bank_mask:0xf
	v_add_f32_dpp v89, v76, v76 row_shr:8 row_mask:0xf bank_mask:0xf bound_ctrl:1
	v_mov_b32_dpp v76, v136 row_shr:1 row_mask:0xf bank_mask:0xf bound_ctrl:1
	v_fmac_f32_e32 v76, 0xbf1b4598, v135
	v_mul_f32_e32 v87, 0x3fb8aa3b, v89
	v_exp_f32_e32 v91, v87
	v_add_f32_dpp v76, v76, v76 row_shr:2 row_mask:0xf bank_mask:0xf bound_ctrl:1
	v_pk_mul_f32 v[84:85], v[84:85], v[88:89] op_sel_hi:[1,0]
	v_lshlrev_b32_e32 v104, 16, v105
	v_add_f32_dpp v76, v76, v76 row_shr:4 row_mask:0xf bank_mask:0xf bound_ctrl:1
; #define LAS __attribute__((address_space(3)))
; #define MFMA16(a, b, c) __builtin_amdgcn_mfma_f32_16x16x16bf16_1k(a, b, c, 0, 0, 0)
; __device__ void phase_rwkv_dist(const Params& p, LAS unsigned char* lds, int wg, int nwg) {
;     ...
;                 for (int nt = 0; nt < 4; ++nt) {
;                     const f32x4 w0 = *(LAS const f32x4*)(cq + 0 * 64 + 16 * nt), a0 = *(LAS const f32x4*)(cq + 1 * 64 + 16 * nt);
;                     f32x4 lw, ag;
; #pragma unroll
;                     for (int i = 0; i < 4; ++i) { lw[i] = -0.60653066f * __builtin_amdgcn_rcpf(1.f + __expf(-(w0[i] + accw[nt][i]))); ag[i] = __builtin_amdgcn_rcpf(1.f + __expf(-(a0[i] + acca[nt][i]))); }
;                     const f32x4 mur = *(LAS const f32x4*)(cq + 5 * 64 + 16 * nt), muk = *(LAS const f32x4*)(cq + 6 * 64 + 16 * nt), kkc = *(LAS const f32x4*)(cq + 2 * 64 + 16 * nt), kac = *(LAS const f32x4*)(cq + 3 * 64 + 16 * nt), rkc = *(LAS const f32x4*)(cq + 4 * 64 + 16 * nt);
;                     const f32x4 rc = up4(nX[nt][0]), kc = up4(nX[4 + nt][0]); f32x4 rp = up4(nX[nt][1]), kq = up4(nX[4 + nt][1]); if (first) { rp = zero4; kq = zero4; }
;                     const f32x4 r4 = rc + (rp - rc) * mur, k4 = kc + (kq - kc) * muk;
;                     const f32x4 kn = k4 * kkc * rn, kp = k4 * (1.f + (ag - 1.f) * kac);
;                     const f32x4 b4_ = r4 * kp * rkc; bo += (b4_.x + b4_.y) + (b4_.z + b4_.w);
;                     f32x4 G = lw;
; #pragma unroll
;                     for (int i = 0; i < 4; ++i) { float g = G[i]; g += dpp_f<0x111>(g); g += dpp_f<0x112>(g); g += dpp_f<0x114>(g); g += dpp_f<0x118>(g); G[i] = g; }
;                     f32x4 eG, eGx, eI;
; #pragma unroll
;                     for (int i = 0; i < 4; ++i) { eG[i] = __expf(G[i]); eGx[i] = __builtin_bit_cast(float, __builtin_amdgcn_update_dpp(0x3F800000, __builtin_bit_cast(int, eG[i]), 0x111, 0xf, 0xf, false)); eI[i] = __builtin_amdgcn_rcpf(eG[i]); }
;                     qa[nt] = pk4((zero4 - kn) * eGx); qb[nt] = pk4(kn * ag * eI); qk[nt] = pk4(kp * eI); qr[nt] = pk4(r4 * eG);
;                     __builtin_amdgcn_raw_buffer_store_b128(__builtin_bit_cast(u32x4, eG), rsWS, (r == 15) ? (16 * nt + 4 * q) * 4 : 0x7ffffff0, so + 10240, 16);
;                     const f32x4 d1 = MFMA16(qb[nt], ident, zero4), d2 = MFMA16(qk[nt], ident, zero4);
	v_rcp_f32_e32 v119, v91
	v_and_b32_e32 v105, 0xffff0000, v105
	v_add_f32_dpp v92, v76, v76 row_shr:8 row_mask:0xf bank_mask:0xf bound_ctrl:1
	v_mov_b32_dpp v76, v142 row_shr:1 row_mask:0xf bank_mask:0xf bound_ctrl:1
	v_fmac_f32_e32 v76, 0xbf1b4598, v137
	v_mul_f32_e32 v87, 0x3fb8aa3b, v92
	v_exp_f32_e32 v92, v87
	v_add_f32_dpp v76, v76, v76 row_shr:2 row_mask:0xf bank_mask:0xf bound_ctrl:1
	v_pk_mul_f32 v[80:81], v[80:81], v[118:119]
	v_cndmask_b32_e64 v126, v126, 0, s[38:39]
	v_add_f32_dpp v76, v76, v76 row_shr:4 row_mask:0xf bank_mask:0xf bound_ctrl:1
	v_rcp_f32_e32 v120, v92
	v_cvt_pk_bf16_f32 v80, v80, v81
	v_add_f32_dpp v93, v76, v76 row_shr:8 row_mask:0xf bank_mask:0xf bound_ctrl:1
	v_mul_f32_e32 v87, 0x3fb8aa3b, v93
	v_exp_f32_e32 v93, v87
	v_pk_mul_f32 v[76:77], v[0:1], v[82:83] op_sel_hi:[0,1]
	v_pk_fma_f32 v[82:83], v[0:1], v[82:83], 0 op_sel_hi:[0,1,0] neg_lo:[1,0,0] neg_hi:[1,0,0]
	v_pk_mul_f32 v[82:83], v[82:83], v[88:89] op_sel_hi:[1,0]
	v_rcp_f32_e32 v121, v93
	v_cvt_pk_bf16_f32 v89, v82, v83
	v_pk_mul_f32 v[82:83], v[94:95], v[96:97]
	v_pk_mul_f32 v[76:77], v[76:77], v[98:99]
	v_cvt_pk_bf16_f32 v88, v84, v85
	v_pk_mul_f32 v[84:85], v[76:77], v[120:121]
	v_pk_mul_f32 v[76:77], v[82:83], v[118:119]
	v_pk_mul_f32 v[82:83], v[102:103], v[120:121]
	v_cvt_pk_bf16_f32 v76, v76, v77
	v_cvt_pk_bf16_f32 v77, v84, v85
	v_cvt_pk_bf16_f32 v81, v82, v83
	v_pk_mul_f32 v[78:79], v[78:79], v[92:93]
	v_pk_mul_f32 v[82:83], v[100:101], v[90:91]
	s_cmp_eq_u32 s91, 0
	s_cbranch_scc1 .Lrst4s
	buffer_store_dwordx4 v[90:93], v212, s[52:55], s6 offen
	s_branch .Lrst4d
.Lrst4s:
	buffer_store_dwordx4 v[90:93], v212, s[52:55], s6 offen sc1
.Lrst4d:
	v_mfma_f32_16x16x16_bf16 v[90:93], v[76:77], v[150:151], 0
	v_cvt_pk_bf16_f32 v85, v78, v79
	v_cvt_pk_bf16_f32 v84, v82, v83
	v_cndmask_b32_e64 v127, v107, 0, s[38:39]
	v_mfma_f32_16x16x16_bf16 v[94:97], v[80:81], v[150:151], 0
	v_cndmask_b32_e64 v123, v123, 0, s[38:39]
	s_nop 2
	v_cvt_pk_bf16_f32 v90, v90, v91
	v_cvt_pk_bf16_f32 v91, v92, v93
	v_cndmask_b32_e64 v106, v106, 0, s[38:39]
	v_sub_f32_e32 v107, v106, v125
	v_cvt_pk_bf16_f32 v92, v94, v95
	v_cvt_pk_bf16_f32 v93, v96, v97
	s_cmp_eq_u32 s91, 0
	s_cbranch_scc1 .Lrst5s
	buffer_store_dwordx4 v[90:93], v213, s[52:55], s3 offen
	s_branch .Lrst5d
.Lrst5s:
	buffer_store_dwordx4 v[90:93], v213, s[52:55], s3 offen sc1
.Lrst5d:
	ds_read_b128 v[90:93], v139 offset:192
	ds_read_b128 v[94:97], v139 offset:448
	v_sub_f32_e32 v106, v123, v124
	v_sub_f32_e32 v127, v127, v105
	v_sub_f32_e32 v126, v126, v104
	s_waitcnt lgkmcnt(1)
	v_add_f32_e32 v68, v68, v90
	v_mul_f32_e32 v68, 0xbfb8aa3b, v68
	v_exp_f32_e32 v68, v68
	v_add_f32_e32 v86, v130, v86
	v_add_f32_e32 v68, 1.0, v68
	v_rcp_f32_e32 v87, v68
	s_waitcnt lgkmcnt(0)
	v_add_f32_e32 v68, v72, v94
	v_mul_f32_e32 v68, 0xbfb8aa3b, v68
	v_exp_f32_e32 v68, v68
	v_mul_f32_e32 v102, 0xbf1b4598, v87
	v_add_f32_e32 v68, 1.0, v68
	v_rcp_f32_e32 v78, v68
	v_add_f32_e32 v68, v69, v91
	v_mul_f32_e32 v68, 0xbfb8aa3b, v68
	v_exp_f32_e32 v68, v68
	s_nop 0
	v_add_f32_e32 v68, 1.0, v68
	v_rcp_f32_e32 v103, v68
	v_add_f32_e32 v68, v73, v95
	v_mul_f32_e32 v68, 0xbfb8aa3b, v68
	v_exp_f32_e32 v68, v68
	v_mul_f32_e32 v118, 0xbf1b4598, v103
	v_add_f32_e32 v68, 1.0, v68
	v_rcp_f32_e32 v79, v68
	v_add_f32_e32 v68, v70, v92
	v_mul_f32_e32 v68, 0xbfb8aa3b, v68
	v_exp_f32_e32 v68, v68
	s_nop 0
	v_add_f32_e32 v68, 1.0, v68
	v_rcp_f32_e32 v119, v68
	v_add_f32_e32 v68, v74, v96
	v_mul_f32_e32 v68, 0xbfb8aa3b, v68
	v_exp_f32_e32 v68, v68
	v_mul_f32_e32 v120, 0xbf1b4598, v119
	v_add_f32_e32 v68, 1.0, v68
	v_rcp_f32_e32 v82, v68
	v_add_f32_e32 v68, v71, v93
	v_mul_f32_e32 v68, 0xbfb8aa3b, v68
	v_exp_f32_e32 v68, v68
	s_nop 0
	v_add_f32_e32 v68, 1.0, v68
	v_rcp_f32_e32 v121, v68
	v_add_f32_e32 v68, v75, v97
	v_mul_f32_e32 v68, 0xbfb8aa3b, v68
	v_exp_f32_e32 v68, v68
	v_mul_f32_e32 v122, 0xbf1b4598, v121
	v_add_f32_e32 v68, 1.0, v68
	v_rcp_f32_e32 v83, v68
	ds_read_b128 v[68:71], v139 offset:1472
	ds_read_b128 v[72:75], v139 offset:1728
	ds_read_b128 v[90:93], v139 offset:704
	ds_read_b128 v[94:97], v139 offset:960
	ds_read_b128 v[98:101], v139 offset:1216
	s_waitcnt lgkmcnt(4)
	v_pk_fma_f32 v[104:105], v[126:127], v[70:71], v[104:105]
	v_pk_fma_f32 v[106:107], v[106:107], v[68:69], v[124:125]
	s_waitcnt lgkmcnt(3)
	v_pk_fma_f32 v[68:69], v[114:115], v[74:75], v[112:113]
	v_pk_fma_f32 v[70:71], v[116:117], v[72:73], v[110:111]
	s_waitcnt lgkmcnt(2)
	v_pk_mul_f32 v[72:73], v[92:93], v[68:69]
	v_pk_mul_f32 v[74:75], v[90:91], v[70:71]
	v_pk_add_f32 v[90:91], v[82:83], -1.0 op_sel_hi:[1,0]
	v_pk_add_f32 v[92:93], v[78:79], -1.0 op_sel_hi:[1,0]
	s_waitcnt lgkmcnt(1)
	v_pk_fma_f32 v[90:91], v[96:97], v[90:91], 1.0 op_sel_hi:[1,1,0]
	v_pk_fma_f32 v[92:93], v[94:95], v[92:93], 1.0 op_sel_hi:[1,1,0]
	v_pk_mul_f32 v[94:95], v[68:69], v[90:91]
	v_pk_mul_f32 v[92:93], v[70:71], v[92:93]
	v_pk_mul_f32 v[70:71], v[104:105], v[94:95]
	v_pk_mul_f32 v[68:69], v[106:107], v[92:93]
	s_waitcnt lgkmcnt(0)
; #define LAS __attribute__((address_space(3)))
; #define MFMA16(a, b, c) __builtin_amdgcn_mfma_f32_16x16x16bf16_1k(a, b, c, 0, 0, 0)
; __device__ void phase_rwkv_dist(const Params& p, LAS unsigned char* lds, int wg, int nwg) {
;     ...
;                 for (int nt = 0; nt < 4; ++nt) {
;                     const f32x4 w0 = *(LAS const f32x4*)(cq + 0 * 64 + 16 * nt), a0 = *(LAS const f32x4*)(cq + 1 * 64 + 16 * nt);
;                     f32x4 lw, ag;
; #pragma unroll
;                     for (int i = 0; i < 4; ++i) { lw[i] = -0.60653066f * __builtin_amdgcn_rcpf(1.f + __expf(-(w0[i] + accw[nt][i]))); ag[i] = __builtin_amdgcn_rcpf(1.f + __expf(-(a0[i] + acca[nt][i]))); }
;                     const f32x4 mur = *(LAS const f32x4*)(cq + 5 * 64 + 16 * nt), muk = *(LAS const f32x4*)(cq + 6 * 64 + 16 * nt), kkc = *(LAS const f32x4*)(cq + 2 * 64 + 16 * nt), kac = *(LAS const f32x4*)(cq + 3 * 64 + 16 * nt), rkc = *(LAS const f32x4*)(cq + 4 * 64 + 16 * nt);
;                     const f32x4 rc = up4(nX[nt][0]), kc = up4(nX[4 + nt][0]); f32x4 rp = up4(nX[nt][1]), kq = up4(nX[4 + nt][1]); if (first) { rp = zero4; kq = zero4; }
;                     const f32x4 r4 = rc + (rp - rc) * mur, k4 = kc + (kq - kc) * muk;
;                     const f32x4 kn = k4 * kkc * rn, kp = k4 * (1.f + (ag - 1.f) * kac);
;                     const f32x4 b4_ = r4 * kp * rkc; bo += (b4_.x + b4_.y) + (b4_.z + b4_.w);
;                     f32x4 G = lw;
; #pragma unroll
;                     for (int i = 0; i < 4; ++i) { float g = G[i]; g += dpp_f<0x111>(g); g += dpp_f<0x112>(g); g += dpp_f<0x114>(g); g += dpp_f<0x118>(g); G[i] = g; }
;                     f32x4 eG, eGx, eI;
; #pragma unroll
;                     for (int i = 0; i < 4; ++i) { eG[i] = __expf(G[i]); eGx[i] = __builtin_bit_cast(float, __builtin_amdgcn_update_dpp(0x3F800000, __builtin_bit_cast(int, eG[i]), 0x111, 0xf, 0xf, false)); eI[i] = __builtin_amdgcn_rcpf(eG[i]); }
;                     qa[nt] = pk4((zero4 - kn) * eGx); qb[nt] = pk4(kn * ag * eI); qk[nt] = pk4(kp * eI); qr[nt] = pk4(r4 * eG);
;                     __builtin_amdgcn_raw_buffer_store_b128(__builtin_bit_cast(u32x4, eG), rsWS, (r == 15) ? (16 * nt + 4 * q) * 4 : 0x7ffffff0, so + 10240, 16);
;                     const f32x4 d1 = MFMA16(qb[nt], ident, zero4), d2 = MFMA16(qk[nt], ident, zero4);
	v_pk_mul_f32 v[70:71], v[100:101], v[70:71]
	v_pk_mul_f32 v[68:69], v[98:99], v[68:69]
	v_mov_b32_e32 v90, 1.0
	v_add_f32_e32 v68, v68, v69
	v_add_f32_e32 v69, v70, v71
	v_add_f32_e32 v91, v68, v69
	v_mov_b32_dpp v68, v102 row_shr:1 row_mask:0xf bank_mask:0xf bound_ctrl:1
	v_mov_b32_dpp v69, v118 row_shr:1 row_mask:0xf bank_mask:0xf bound_ctrl:1
	v_mov_b32_dpp v70, v120 row_shr:1 row_mask:0xf bank_mask:0xf bound_ctrl:1
	v_mov_b32_dpp v71, v122 row_shr:1 row_mask:0xf bank_mask:0xf bound_ctrl:1
	v_fmac_f32_e32 v68, 0xbf1b4598, v87
	v_fmac_f32_e32 v69, 0xbf1b4598, v103
	v_fmac_f32_e32 v70, 0xbf1b4598, v119
	v_fmac_f32_e32 v71, 0xbf1b4598, v121
	v_add_f32_dpp v68, v68, v68 row_shr:2 row_mask:0xf bank_mask:0xf bound_ctrl:1
	v_add_f32_dpp v69, v69, v69 row_shr:2 row_mask:0xf bank_mask:0xf bound_ctrl:1
	v_add_f32_dpp v70, v70, v70 row_shr:2 row_mask:0xf bank_mask:0xf bound_ctrl:1
	v_add_f32_dpp v71, v71, v71 row_shr:2 row_mask:0xf bank_mask:0xf bound_ctrl:1
	v_add_f32_dpp v68, v68, v68 row_shr:4 row_mask:0xf bank_mask:0xf bound_ctrl:1
	v_add_f32_dpp v69, v69, v69 row_shr:4 row_mask:0xf bank_mask:0xf bound_ctrl:1
	v_add_f32_dpp v70, v70, v70 row_shr:4 row_mask:0xf bank_mask:0xf bound_ctrl:1
	v_add_f32_dpp v71, v71, v71 row_shr:4 row_mask:0xf bank_mask:0xf bound_ctrl:1
	v_add_f32_dpp v68, v68, v68 row_shr:8 row_mask:0xf bank_mask:0xf bound_ctrl:1
	v_add_f32_dpp v69, v69, v69 row_shr:8 row_mask:0xf bank_mask:0xf bound_ctrl:1
	v_add_f32_dpp v70, v70, v70 row_shr:8 row_mask:0xf bank_mask:0xf bound_ctrl:1
	v_add_f32_dpp v71, v71, v71 row_shr:8 row_mask:0xf bank_mask:0xf bound_ctrl:1
	v_mul_f32_e32 v68, 0x3fb8aa3b, v68
	v_mul_f32_e32 v69, 0x3fb8aa3b, v69
	v_mul_f32_e32 v70, 0x3fb8aa3b, v70
	v_mul_f32_e32 v71, 0x3fb8aa3b, v71
	v_exp_f32_e32 v68, v68
	v_exp_f32_e32 v69, v69
	v_exp_f32_e32 v70, v70
	v_exp_f32_e32 v71, v71
	v_rcp_f32_e32 v100, v68
	v_rcp_f32_e32 v101, v69
	v_rcp_f32_e32 v102, v70
	v_rcp_f32_e32 v103, v71
	v_pk_mul_f32 v[96:97], v[0:1], v[72:73] op_sel_hi:[0,1]
	v_pk_mul_f32 v[98:99], v[0:1], v[74:75] op_sel_hi:[0,1]
	v_mov_b32_dpp v90, v68 row_shr:1 row_mask:0xf bank_mask:0xf
	v_pk_fma_f32 v[72:73], v[0:1], v[72:73], 0 op_sel_hi:[0,1,0] neg_lo:[1,0,0] neg_hi:[1,0,0]
	v_pk_fma_f32 v[74:75], v[0:1], v[74:75], 0 op_sel_hi:[0,1,0] neg_lo:[1,0,0] neg_hi:[1,0,0]
	v_pk_mul_f32 v[72:73], v[72:73], v[90:91] op_sel_hi:[1,0]
	v_pk_mul_f32 v[74:75], v[74:75], v[90:91] op_sel_hi:[1,0]
	v_add_f32_e32 v110, v86, v91
	v_cvt_pk_bf16_f32 v90, v74, v75
	v_cvt_pk_bf16_f32 v91, v72, v73
	v_pk_mul_f32 v[72:73], v[98:99], v[78:79]
	v_pk_mul_f32 v[74:75], v[96:97], v[82:83]
	v_pk_mul_f32 v[72:73], v[72:73], v[100:101]
	v_pk_mul_f32 v[74:75], v[74:75], v[102:103]
	v_cvt_pk_bf16_f32 v78, v72, v73
	v_cvt_pk_bf16_f32 v79, v74, v75
	v_pk_mul_f32 v[72:73], v[94:95], v[102:103]
	v_pk_mul_f32 v[74:75], v[92:93], v[100:101]
	v_cvt_pk_bf16_f32 v83, v72, v73
	v_cvt_pk_bf16_f32 v82, v74, v75
	v_pk_mul_f32 v[72:73], v[104:105], v[70:71]
	v_pk_mul_f32 v[74:75], v[106:107], v[68:69]
	ds_bpermute_b32 v0, v141, v110
	v_cvt_pk_bf16_f32 v86, v74, v75
	v_cvt_pk_bf16_f32 v87, v72, v73
	s_cmp_eq_u32 s91, 0
	s_cbranch_scc1 .Lrst6s
	buffer_store_dwordx4 v[68:71], v214, s[52:55], s6 offen
	s_branch .Lrst6d
.Lrst6s:
	buffer_store_dwordx4 v[68:71], v214, s[52:55], s6 offen sc1
.Lrst6d:
	v_mfma_f32_16x16x16_bf16 v[68:71], v[78:79], v[150:151], 0
	s_waitcnt lgkmcnt(0)
	v_add_f32_e32 v0, v110, v0
	v_mfma_f32_16x16x16_bf16 v[72:75], v[82:83], v[150:151], 0
	s_nop 4
	v_cvt_pk_bf16_f32 v68, v68, v69
	v_cvt_pk_bf16_f32 v69, v70, v71
	s_nop 0
	v_cvt_pk_bf16_f32 v70, v72, v73
	v_cvt_pk_bf16_f32 v71, v74, v75
	s_cmp_eq_u32 s91, 0
	s_cbranch_scc1 .Lrst7s
	buffer_store_dwordx4 v[68:71], v215, s[52:55], s3 offen
	s_branch .Lrst7d
.Lrst7s:
	buffer_store_dwordx4 v[68:71], v215, s[52:55], s3 offen sc1
.Lrst7d:
	ds_bpermute_b32 v68, v140, v0
	s_add_i32 s3, s2, 0x800
	s_waitcnt lgkmcnt(0)
	v_add_f32_e32 v0, v0, v68
	v_lshlrev_b64 v[68:69], 8, v[108:109]
	v_lshl_add_u64 v[68:69], s[58:59], 0, v[68:69]
	global_store_dwordx2 v[68:69], v[0:1], off
	s_cmp_eq_u32 s91, 0
	s_cbranch_scc1 .Lrst8s
	buffer_store_dwordx4 v[64:67], v196, s[52:55], s2 offen
	s_branch .Lrst8d
.Lrst8s:
	buffer_store_dwordx4 v[64:67], v196, s[52:55], s2 offen sc1
.Lrst8d:
	s_cmp_eq_u32 s91, 0
	s_cbranch_scc1 .Lrst9s
	buffer_store_dwordx4 v[88:91], v197, s[52:55], s2 offen
	s_branch .Lrst9d
.Lrst9s:
	buffer_store_dwordx4 v[88:91], v197, s[52:55], s2 offen sc1
.Lrst9d:
	s_cmp_eq_u32 s91, 0
	s_cbranch_scc1 .Lrst10s
	buffer_store_dwordx4 v[60:63], v196, s[52:55], s3 offen
	s_branch .Lrst10d
.Lrst10s:
	buffer_store_dwordx4 v[60:63], v196, s[52:55], s3 offen sc1
.Lrst10d:
	s_cmp_eq_u32 s91, 0
	s_cbranch_scc1 .Lrst11s
	buffer_store_dwordx4 v[84:87], v197, s[52:55], s3 offen
	s_branch .Lrst11d

; __device__ __forceinline__ bf16x4 pk4(f32x4 v) { u32x2 w; w.x = pg8::cvt_pk_bf16_c(v.x, v.y); w.y = pg8::cvt_pk_bf16_c(v.z, v.w); return __builtin_bit_cast(bf16x4, w); }
; #define MFMA16(a, b, c) __builtin_amdgcn_mfma_f32_16x16x16bf16_1k(a, b, c, 0, 0, 0)
; #define MFMA32(a, b, c) __builtin_amdgcn_mfma_f32_16x16x32_bf16(a, b, c, 0, 0, 0)
; __device__ void phase_rwkv_dist(const Params& p, LAS unsigned char* lds, int wg, int nwg) {
;     ...
;                 f32x4 mab = MFMA32(pb0, pa0, zero4); mab = MFMA32(pb1, pa1, mab);
;                 f32x4 mak = MFMA32(pk0, pa0, zero4); mak = MFMA32(pk1, pa1, mak);
;                 f32x4 mrb = MFMA32(pb0, pr0, zero4); mrb = MFMA32(pb1, pr1, mrb);
;                 f32x4 mrk = MFMA32(pk0, pr0, zero4); mrk = MFMA32(pk1, pr1, mrk);
; #pragma unroll
;                 for (int t = 0; t < 4; ++t) { const int j = 4 * q + t; if (!(j < r)) { mab[t] = 0.f; mak[t] = 0.f; } if (!(j <= r)) { mrb[t] = 0.f; mrk[t] = 0.f; } }
;                 { const bf16x4 e1 = pk4(mak), e2 = pk4(mrb); __builtin_amdgcn_raw_buffer_store_b128(__builtin_bit_cast(u32x4, __builtin_shufflevector(e1, e2, 0, 1, 2, 3, 4, 5, 6, 7)), rsWS, lane * 32, so + RD_MM, 16); }
;                 const bf16x4 mrkp = pk4(mrk);
;                 __builtin_amdgcn_sched_barrier(0);
;                 {   const bf16x4 nA = pk4(mab);
;                     const bf16x4 nB = pk4(MFMA16(nA, ident, zero4));
;                     f32x4 s;
; #pragma unroll
;                     for (int t = 0; t < 4; ++t) s[t] = mab[t] + ((4 * q + t == r) ? 1.f : 0.f);
;                     const bf16x4 z2a = pk4(MFMA16(nA, nB, zero4)), z2b = pk4(MFMA16(nB, nA, zero4));
;                     s = MFMA16(z2a, pk4(s), s);
;                     const bf16x4 z4a = pk4(MFMA16(z2b, z2a, zero4)), z4b = pk4(MFMA16(z2a, z2b, zero4));
;                     s = MFMA16(z4a, pk4(s), s);
;                     const bf16x4 z8a = pk4(MFMA16(z4b, z4a, zero4));
;                     s = MFMA16(z8a, pk4(s), s);
;                     { const bf16x4 e2 = pk4(s); __builtin_amdgcn_raw_buffer_store_b128(__builtin_bit_cast(u32x4, __builtin_shufflevector(mrkp, e2, 0, 1, 2, 3, 4, 5, 6, 7)), rsWS, lane * 32 + 16, so + RD_MM, 16); }
.Lrst11d:
	v_mfma_f32_16x16x32_bf16 v[68:71], v[52:55], v[64:67], 0
	v_mov_b32_e32 v0, s73
	s_or_b64 vcc, s[30:31], s[22:23]
	s_addk_i32 s2, 0x2000
	v_mfma_f32_16x16x32_bf16 v[64:67], v[56:59], v[64:67], 0
	v_mfma_f32_16x16x32_bf16 v[52:55], v[52:55], v[60:63], 0
	v_mfma_f32_16x16x32_bf16 v[56:59], v[56:59], v[60:63], 0
	v_mov_b32_e32 v60, s73
	v_mfma_f32_16x16x32_bf16 v[52:55], v[76:79], v[84:87], v[52:55]
	v_mfma_f32_16x16x32_bf16 v[56:59], v[80:83], v[84:87], v[56:59]
	v_mfma_f32_16x16x32_bf16 v[64:67], v[80:83], v[88:91], v[64:67]
	s_nop 5
	v_cndmask_b32_e64 v0, v52, v0, s[24:25]
	v_cndmask_b32_e64 v60, v56, v60, s[24:25]
	v_cndmask_b32_e64 v0, v0, v52, s[22:23]
	v_mfma_f32_16x16x32_bf16 v[68:71], v[76:79], v[88:91], v[68:71]
	v_cndmask_b32_e64 v61, 0, v53, s[22:23]
	v_cndmask_b32_e64 v56, v60, v56, s[22:23]
	v_cndmask_b32_e64 v60, v54, 0, s[34:35]
	v_cndmask_b32_e64 v53, 0, v67, s[26:27]
	v_cndmask_b32_e64 v54, 0, v66, s[28:29]
	v_cndmask_b32_e64 v52, 0, v65, s[30:31]
	v_cndmask_b32_e32 v62, 0, v64, vcc
	v_cndmask_b32_e64 v55, v55, 0, s[36:37]
	v_cndmask_b32_e64 v57, 0, v57, s[22:23]
	v_cndmask_b32_e64 v58, v58, 0, s[34:35]
	v_cndmask_b32_e64 v59, v59, 0, s[36:37]
	v_cvt_pk_bf16_f32 v52, v62, v52
	v_cvt_pk_bf16_f32 v53, v54, v53
	v_cvt_pk_bf16_f32 v54, v0, v61
	v_cvt_pk_bf16_f32 v55, v60, v55
	v_cndmask_b32_e64 v71, 0, v71, s[26:27]
	v_cndmask_b32_e64 v70, 0, v70, s[28:29]
	v_cndmask_b32_e64 v69, 0, v69, s[30:31]
	v_cndmask_b32_e32 v68, 0, v68, vcc
	s_cmp_eq_u32 s91, 0
	s_cbranch_scc1 .Lrst12s
	buffer_store_dwordx4 v[52:55], v198, s[52:55], s2 offen
	s_branch .Lrst12d
.Lrst12s:
	buffer_store_dwordx4 v[52:55], v198, s[52:55], s2 offen sc1
.Lrst12d:
	v_cvt_pk_bf16_f32 v52, v56, v57
	v_cvt_pk_bf16_f32 v53, v58, v59
	v_cvt_pk_bf16_f32 v62, v68, v69
	v_cvt_pk_bf16_f32 v63, v70, v71
	s_ashr_i32 s63, s62, 31
	s_nop 0
	v_mfma_f32_16x16x16_bf16 v[54:57], v[62:63], v[150:151], 0
	s_nop 7
	v_cvt_pk_bf16_f32 v64, v54, v55
	v_cvt_pk_bf16_f32 v65, v56, v57
	v_add_f32_e32 v54, v216, v68
	v_add_f32_e32 v55, v187, v69
	v_mfma_f32_16x16x16_bf16 v[58:61], v[62:63], v[64:65], 0
	v_add_f32_e32 v56, v217, v70
	v_add_f32_e32 v57, v188, v71
	s_nop 5
	v_cvt_pk_bf16_f32 v66, v58, v59
	v_cvt_pk_bf16_f32 v67, v60, v61
	v_mfma_f32_16x16x16_bf16 v[58:61], v[64:65], v[62:63], 0
	s_nop 7
	v_cvt_pk_bf16_f32 v62, v58, v59
	v_cvt_pk_bf16_f32 v63, v60, v61
	v_cvt_pk_bf16_f32 v58, v54, v55
	v_cvt_pk_bf16_f32 v59, v56, v57
	s_nop 1
	v_mfma_f32_16x16x16_bf16 v[54:57], v[66:67], v[58:59], v[54:57]
	v_mfma_f32_16x16x16_bf16 v[58:61], v[62:63], v[66:67], 0
	s_nop 7
	v_cvt_pk_bf16_f32 v64, v58, v59
	v_cvt_pk_bf16_f32 v65, v60, v61
	v_mfma_f32_16x16x16_bf16 v[58:61], v[66:67], v[62:63], 0
	s_nop 7
	v_cvt_pk_bf16_f32 v58, v58, v59
	v_cvt_pk_bf16_f32 v59, v60, v61
	v_cvt_pk_bf16_f32 v60, v54, v55
	v_cvt_pk_bf16_f32 v61, v56, v57
	s_nop 1
	v_mfma_f32_16x16x16_bf16 v[54:57], v[64:65], v[60:61], v[54:57]
	v_mfma_f32_16x16x16_bf16 v[58:61], v[58:59], v[64:65], 0
	s_nop 7
	v_cvt_pk_bf16_f32 v58, v58, v59
	v_cvt_pk_bf16_f32 v59, v60, v61
	v_cvt_pk_bf16_f32 v60, v54, v55
	v_cvt_pk_bf16_f32 v61, v56, v57
	s_nop 1
	v_mfma_f32_16x16x16_bf16 v[54:57], v[58:59], v[60:61], v[54:57]
	s_nop 7
	v_cvt_pk_bf16_f32 v54, v54, v55
	v_cvt_pk_bf16_f32 v55, v56, v57
	s_cmp_eq_u32 s91, 0
	s_cbranch_scc1 .Lrst13s
	buffer_store_dwordx4 v[52:55], v199, s[52:55], s2 offen
	s_branch .Lrst13d
.Lrst13s:
	buffer_store_dwordx4 v[52:55], v199, s[52:55], s2 offen sc1
.Lrst13d:
	s_mov_b32 s90, s62

; #define RD_PEEK(cc) __hip_atomic_load(READY + bh * 512 + (cc), __ATOMIC_RELAXED, __HIP_MEMORY_SCOPE_AGENT)
; __device__ void phase_rwkv_dist(const Params& p, LAS unsigned char* lds, int wg, int nwg) {
;     ...
;             bf16_t* SS = (bf16_t*)p.out; const float* CD = (const float*)(p.ws + WS_CTL + WS_CD);
;             const int nitem = (BATCH * 32 * 64 * 32 + nwg * 64 - 1) / (nwg * 64), nstep = ((nitem + 3) / 4) * 128;
;             const int per = (nitem + 3) / 4;
;             int s2 = (unit == wg) ? 0 : nstep; f32x4 hh = zero4;
;             RD_ISSUE(fw, 0, 0u);
;             for (int c2 = fw; c2 < RC_NCHK; c2 += 8) {
;                 const unsigned pr1 = RD_PEEK(c2 + 4), pr0 = (c2 + 8 < RC_NCHK) ? RD_PEEK(c2 + 8) : 0u;
;                 u32x2 raw[4]; float dd[4]; bf16_t* qq[4]; bool ok[4];
; #pragma unroll
;                 for (int k = 0; k < 4; ++k) { const int ss = s2 + k, item = fw * per + (ss >> 7), cc = ss & 127, idx = item * (nwg * 64) + wg * 64 + lane; ok[k] = ss < nstep && (ss >> 7) < per && item < nitem && idx < BATCH * 32 * 64 * 32;
;                     const int n4 = idx & 31, pp = (idx >> 5) & 63, eg = (idx >> 11) & 31, bb = idx >> 16;
;                     qq[k] = SS + ((((size_t)bb * 128 + cc) * 32 + eg) * 64 + pp) * 128 + 4 * n4; raw[k] = (u32x2){0u, 0u}; dd[k] = 0.f;
;                     if (ok[k]) { raw[k] = *(const u32x2*)qq[k]; dd[k] = CD[(bb * 128 + cc) * 32 + eg]; } }
.LBB0_681:
	v_readlane_b32 s6, v253, 51
	s_cmp_lg_u32 s51, s6
	v_readlane_b32 s6, v254, 18
	v_readlane_b32 s7, v254, 19
	s_cselect_b32 s81, s56, 0
	s_andn2_b64 vcc, exec, s[6:7]
	s_cbranch_vccnz .LBB0_769
	v_writelane_b32 v254, s72, 46
	s_lshl_b32 s84, s94, 20
	v_readlane_b32 s6, v254, 14
	s_add_i32 s6, s80, s6
	s_add_i32 s7, s6, 0x2000
	buffer_load_dwordx4 v[80:83], v197, s[52:55], s7 offen sc1
	buffer_load_dwordx4 v[72:75], v196, s[52:55], s7 offen sc1
	s_add_i32 s7, s6, 0x1000
	buffer_load_dwordx4 v[88:91], v215, s[52:55], s7 offen sc1
	buffer_load_dwordx4 v[84:87], v213, s[52:55], s7 offen sc1
	buffer_load_dwordx4 v[96:99], v197, s[52:55], s7 offen sc1
	buffer_load_dwordx4 v[92:95], v196, s[52:55], s7 offen sc1
	buffer_load_dwordx4 v[64:67], v215, s[52:55], s6 offen sc1
	buffer_load_dwordx4 v[60:63], v213, s[52:55], s6 offen sc1
	buffer_load_dwordx4 v[68:71], v197, s[52:55], s6 offen sc1
	buffer_load_dwordx4 v[76:79], v196, s[52:55], s6 offen sc1
	v_readlane_b32 s7, v254, 16
	s_add_i32 s7, s84, s7
	s_add_i32 s16, s7, 0xdffff80
	v_or_b32_e32 v0, s40, v200
	s_cmp_gt_i32 s7, 0
	v_lshlrev_b32_e32 v157, 1, v0
	s_cselect_b32 s17, 0, 0xffffff80
	v_add_u32_e32 v0, s17, v157
	s_cselect_b32 s16, s16, 0xe000000
	s_add_i32 s7, s7, 0xe000000
	s_addk_i32 s6, 0x2800
	buffer_load_dwordx2 v[176:177], v0, s[52:55], s16 offen
	buffer_load_dwordx2 v[178:179], v157, s[52:55], s7 offen
	buffer_load_dwordx4 v[100:103], v202, s[52:55], s6 offen sc1
	v_readlane_b32 s6, v254, 0
	s_add_u32 s85, s6, s2
	v_readlane_b32 s2, v254, 2
	v_mov_b32_e32 v2, v1
	v_mov_b32_e32 v3, v1
	s_addc_u32 s86, s2, s3
	v_mov_b32_e32 v0, v1
	v_mov_b64_e32 v[58:59], v[2:3]
	v_readlane_b32 s2, v254, 42
	s_mov_b32 s95, s45
	v_mov_b64_e32 v[56:57], v[0:1]
	s_mov_b32 s72, s2
	v_readlane_b32 s3, v254, 43
	s_lshl_b32 s100, s72, 2
	s_add_u32 s100, s82, s100
	s_addc_u32 s101, s83, 0
	global_load_dword v229, v1, s[100:101] offset:16 sc1
	global_load_dword v230, v1, s[100:101] offset:32 sc1
	s_mov_b32 s99, 0
	s_mov_b32 s32, 0
	v_mov_b32_e32 v2, 0
	s_ashr_i32 s2, s81, 7
	v_readlane_b32 s3, v254, 40
	s_add_i32 s3, s2, s3
	s_mul_i32 s16, s3, s57
	s_add_i32 s16, s16, s33
	s_cmp_lt_i32 s2, s48
	s_cselect_b64 s[46:47], -1, 0
	s_cmp_lt_i32 s3, s20
	s_cselect_b64 s[60:61], -1, 0
	s_ashr_i32 s2, s16, 16
	s_ashr_i32 s3, s2, 31
	s_bfe_u32 s17, s16, 0x5000b
	s_lshl_b64 s[18:19], s[2:3], 12
	s_lshl_b32 s2, s2, 12
	s_or_b32 s88, s18, s17
	s_or_b32 s87, s2, s17
	s_cmp_lt_i32 s81, s56
	s_cselect_b64 s[2:3], -1, 0
	v_or_b32_e32 v0, s16, v165
	s_and_b64 s[2:3], s[2:3], s[46:47]
	v_cmp_gt_i32_e32 vcc, s55, v0
	s_and_b64 s[2:3], s[2:3], s[60:61]
	s_and_b64 s[58:59], s[2:3], vcc
	s_lshl_b32 s2, s81, 5
	v_lshlrev_b32_e32 v0, 3, v0
	s_and_b32 s16, s2, 0xf80
	v_and_b32_e32 v0, 0x3f00, v0
	s_or_b32 s18, s88, s16
	v_lshl_add_u64 v[104:105], v[154:155], 0, v[0:1]
	s_lshl_b64 s[2:3], s[18:19], 14
	v_lshl_add_u64 v[158:159], v[104:105], 0, s[2:3]
	v_mov_b32_e32 v162, 0
	v_mov_b32_e32 v163, 0
	s_and_saveexec_b64 s[2:3], s[58:59]
	s_cbranch_execz .Lssd2p_687
	s_add_i32 s32, s32, 2
	s_or_b32 s16, s87, s16
	s_ashr_i32 s17, s16, 31
	s_lshl_b64 s[16:17], s[16:17], 2
	v_readlane_b32 s62, v253, 54
	v_readlane_b32 s63, v253, 55
	s_add_u32 s16, s62, s16
	s_addc_u32 s17, s63, s17
	global_load_dwordx2 v[162:163], v[158:159], off
	global_load_dword v2, v1, s[16:17]

; #define RD_PEEK(cc) __hip_atomic_load(READY + bh * 512 + (cc), __ATOMIC_RELAXED, __HIP_MEMORY_SCOPE_AGENT)
; __device__ void phase_rwkv_dist(const Params& p, LAS unsigned char* lds, int wg, int nwg) {
;     ...
;             for (int c2 = fw; c2 < RC_NCHK; c2 += 8) {
;                 const unsigned pr1 = RD_PEEK(c2 + 4), pr0 = (c2 + 8 < RC_NCHK) ? RD_PEEK(c2 + 8) : 0u;
;                 u32x2 raw[4]; float dd[4]; bf16_t* qq[4]; bool ok[4];
; #pragma unroll
;                 for (int k = 0; k < 4; ++k) { const int ss = s2 + k, item = fw * per + (ss >> 7), cc = ss & 127, idx = item * (nwg * 64) + wg * 64 + lane; ok[k] = ss < nstep && (ss >> 7) < per && item < nitem && idx < BATCH * 32 * 64 * 32;
;                     const int n4 = idx & 31, pp = (idx >> 5) & 63, eg = (idx >> 11) & 31, bb = idx >> 16;
;                     qq[k] = SS + ((((size_t)bb * 128 + cc) * 32 + eg) * 64 + pp) * 128 + 4 * n4; raw[k] = (u32x2){0u, 0u}; dd[k] = 0.f;
;                     if (ok[k]) { raw[k] = *(const u32x2*)qq[k]; dd[k] = CD[(bb * 128 + cc) * 32 + eg]; } }
;                 RD_ISSUE(c2 + 4, 1, pr1);
.LBB0_683:
	s_lshl_b64 s[40:41], s[72:73], 2
	s_add_u32 s6, s82, s40
	s_addc_u32 s7, s83, s41
	s_cmpk_lt_i32 s72, 0x1f8
	s_cselect_b64 s[44:45], -1, 0
	s_cmpk_gt_i32 s72, 0x1f7
	s_cselect_b64 s[38:39], -1, 0
	s_and_b64 vcc, exec, s[38:39]
	v_mov_b32_e32 v3, 0
	s_add_i32 s100, s99, s32
	s_cmp_eq_u32 s100, 14
	s_cbranch_scc1 .Lfetch_w14
	s_cmp_eq_u32 s100, 13
	s_cbranch_scc1 .Lfetch_w13
	s_cmp_eq_u32 s100, 8
	s_cbranch_scc1 .Lfetch_w8
	s_waitcnt vmcnt(0)
	s_branch .Lfetch_wd

; __device__ void phase_rwkv_dist(const Params& p, LAS unsigned char* lds, int wg, int nwg) {
;     ...
;                 u32x2 raw[4]; float dd[4]; bf16_t* qq[4]; bool ok[4];
; #pragma unroll
;                 for (int k = 0; k < 4; ++k) { const int ss = s2 + k, item = fw * per + (ss >> 7), cc = ss & 127, idx = item * (nwg * 64) + wg * 64 + lane; ok[k] = ss < nstep && (ss >> 7) < per && item < nitem && idx < BATCH * 32 * 64 * 32;
;                     const int n4 = idx & 31, pp = (idx >> 5) & 63, eg = (idx >> 11) & 31, bb = idx >> 16;
;                     qq[k] = SS + ((((size_t)bb * 128 + cc) * 32 + eg) * 64 + pp) * 128 + 4 * n4; raw[k] = (u32x2){0u, 0u}; dd[k] = 0.f;
;                     if (ok[k]) { raw[k] = *(const u32x2*)qq[k]; dd[k] = CD[(bb * 128 + cc) * 32 + eg]; } }
.LBB0_768:
	s_mov_b32 s32, 0
	v_mov_b32_e32 v2, 0
	s_ashr_i32 s2, s81, 7
	v_readlane_b32 s3, v254, 40
	s_add_i32 s3, s2, s3
	s_mul_i32 s16, s3, s57
	s_add_i32 s16, s16, s33
	s_cmp_lt_i32 s2, s48
	s_cselect_b64 s[46:47], -1, 0
	s_cmp_lt_i32 s3, s20
	s_cselect_b64 s[60:61], -1, 0
	s_ashr_i32 s2, s16, 16
	s_ashr_i32 s3, s2, 31
	s_bfe_u32 s17, s16, 0x5000b
	s_lshl_b64 s[18:19], s[2:3], 12
	s_lshl_b32 s2, s2, 12
	s_or_b32 s88, s18, s17
	s_or_b32 s87, s2, s17
	s_cmp_lt_i32 s81, s56
	s_cselect_b64 s[2:3], -1, 0
	v_or_b32_e32 v0, s16, v165
	s_and_b64 s[2:3], s[2:3], s[46:47]
	v_cmp_gt_i32_e32 vcc, s55, v0
	s_and_b64 s[2:3], s[2:3], s[60:61]
	s_and_b64 s[58:59], s[2:3], vcc
	s_lshl_b32 s2, s81, 5
	v_lshlrev_b32_e32 v0, 3, v0
	s_and_b32 s16, s2, 0xf80
	v_and_b32_e32 v0, 0x3f00, v0
	s_or_b32 s18, s88, s16
	v_lshl_add_u64 v[104:105], v[154:155], 0, v[0:1]
	s_lshl_b64 s[2:3], s[18:19], 14
	v_lshl_add_u64 v[158:159], v[104:105], 0, s[2:3]
	v_mov_b32_e32 v162, 0
	v_mov_b32_e32 v163, 0
	s_and_saveexec_b64 s[2:3], s[58:59]
	s_cbranch_execz .LBB0_687
	s_add_i32 s32, s32, 2
	s_or_b32 s16, s87, s16
	s_ashr_i32 s17, s16, 31
	s_lshl_b64 s[16:17], s[16:17], 2
	v_readlane_b32 s62, v253, 54
	v_readlane_b32 s63, v253, 55
	s_add_u32 s16, s62, s16
	s_addc_u32 s17, s63, s17
	global_load_dwordx2 v[162:163], v[158:159], off
	global_load_dword v2, v1, s[16:17]

; __device__ __forceinline__ unsigned cvt_pk_bf16(float lo, float hi) { unsigned r; asm volatile("v_cvt_pk_bf16_f32 %0, %1, %2" : "=v"(r) : "v"(lo), "v"(hi)); return r; }
; __device__ void phase_rwkv_dist(const Params& p, LAS unsigned char* lds, int wg, int nwg) {
;     ...
; #pragma unroll
;                 for (int k = 0; k < 4; ++k) { if (((s2 + k) & 127) == 0) hh = zero4;
;                     if (ok[k]) { u32x2 w; w.x = pg8::cvt_pk_bf16(hh.x, hh.y); w.y = pg8::cvt_pk_bf16(hh.z, hh.w); *(u32x2*)qq[k] = w; hh = hh * dd[k] + up4(raw[k]); } }
;                 s2 += 4;
;             }
.LBB0_693:
	s_or_b64 exec, exec, s[16:17]
	s_mov_b32 s72, s44
	s_branch .LBB0_683
